# speedup vs baseline: 1.0015x; 1.0015x over previous
.LBB0_311:
	v_mov_b32_e32 v14, v190
	s_ashr_i32 s7, s6, 31
	s_lshl_b64 s[8:9], s[6:7], 12
	v_and_b32_e32 v15, 15, v14
	v_lshrrev_b32_e32 v0, 1, v14
	v_and_b32_e32 v2, 24, v0
	v_lshlrev_b32_e32 v0, 12, v15
	v_mov_b32_e32 v1, v129
	v_readlane_b32 s7, v236, 10
	v_lshlrev_b32_e32 v128, 13, v15
	v_mov_b32_e32 v3, v129
	v_add_u32_e32 v2, s7, v2
	v_readlane_b32 s10, v237, 35
	v_lshl_add_u64 v[0:1], s[8:9], 0, v[0:1]
	v_lshl_add_u64 v[4:5], v[2:3], 2, v[128:129]
	v_readlane_b32 s11, v237, 36
	v_lshl_add_u64 v[0:1], v[2:3], 1, v[0:1]
	v_mov_b32_e32 v16, 0
	v_cmp_gt_u32_e32 vcc, 8, v15
	v_lshl_add_u64 v[10:11], s[10:11], 0, v[4:5]
	v_lshl_add_u64 v[12:13], s[4:5], 0, v[0:1]
	v_mov_b32_e32 v40, 0
	v_mov_b32_e32 v41, 0
	v_mov_b32_e32 v42, 0
	v_mov_b32_e32 v43, 0
	v_mov_b32_e32 v44, 0
	v_mov_b32_e32 v45, 0
	v_mov_b32_e32 v46, 0
	v_mov_b32_e32 v47, 0
	v_mov_b32_e32 v48, 0
	v_mov_b32_e32 v49, 0
	v_mov_b32_e32 v50, 0
	v_mov_b32_e32 v51, 0
	v_mov_b32_e32 v52, 0
	v_mov_b32_e32 v53, 0
	v_mov_b32_e32 v54, 0
	v_mov_b32_e32 v55, 0
	v_mov_b32_e32 v56, 0
	v_mov_b32_e32 v57, 0
	v_mov_b32_e32 v58, 0
	v_mov_b32_e32 v59, 0
	v_mov_b32_e32 v60, 0
	v_mov_b32_e32 v61, 0
	v_mov_b32_e32 v62, 0
	v_mov_b32_e32 v63, 0
	v_mov_b32_e32 v64, 0
	v_mov_b32_e32 v65, 0
	v_mov_b32_e32 v66, 0
	v_mov_b32_e32 v67, 0
	v_mov_b32_e32 v68, 0
	v_mov_b32_e32 v69, 0
	v_mov_b32_e32 v70, 0
	v_mov_b32_e32 v71, 0
	s_and_saveexec_b64 s[8:9], vcc
	global_load_dwordx4 v[40:43], v[10:11], off offset:-400
	global_load_dwordx4 v[44:47], v[10:11], off offset:-384
	global_load_dwordx4 v[48:51], v[10:11], off offset:-272
	global_load_dwordx4 v[52:55], v[10:11], off offset:-256
	global_load_dwordx4 v[56:59], v[10:11], off offset:-144
	global_load_dwordx4 v[60:63], v[10:11], off offset:-128
	global_load_dwordx4 v[64:67], v[10:11], off offset:-16
	global_load_dwordx4 v[68:71], v[10:11], off
	s_or_b64 exec, exec, s[8:9]
	global_load_dwordx4 v[72:75], v[12:13], off offset:-128
	global_load_dwordx4 v[76:79], v[12:13], off offset:-64
	global_load_dwordx4 v[80:83], v[12:13], off
	global_load_dwordx4 v[84:87], v[12:13], off offset:64
	s_waitcnt vmcnt(0)
	v_mul_f32_e32 v20, v41, v41
	v_fma_f32 v20, v40, v40, v20
	v_mul_f32_e32 v21, v43, v43
	v_fma_f32 v21, v42, v42, v21
	v_add_f32_e32 v22, v20, v21
	v_mul_f32_e32 v23, v45, v45
	v_fma_f32 v23, v44, v44, v23
	v_mul_f32_e32 v24, v47, v47
	v_fma_f32 v24, v46, v46, v24
	v_add_f32_e32 v25, v23, v24
	v_add_f32_e32 v22, v22, v25
	v_add_f32_e32 v16, v16, v22
	v_mul_f32_e32 v20, v49, v49
	v_fma_f32 v20, v48, v48, v20
	v_mul_f32_e32 v21, v51, v51
	v_fma_f32 v21, v50, v50, v21
	v_add_f32_e32 v22, v20, v21
	v_mul_f32_e32 v23, v53, v53
	v_fma_f32 v23, v52, v52, v23
	v_mul_f32_e32 v24, v55, v55
	v_fma_f32 v24, v54, v54, v24
	v_add_f32_e32 v25, v23, v24
	v_add_f32_e32 v22, v22, v25
	v_add_f32_e32 v16, v16, v22
	v_mul_f32_e32 v20, v57, v57
	v_fma_f32 v20, v56, v56, v20
	v_mul_f32_e32 v21, v59, v59
	v_fma_f32 v21, v58, v58, v21
	v_add_f32_e32 v22, v20, v21
	v_mul_f32_e32 v23, v61, v61
	v_fma_f32 v23, v60, v60, v23
	v_mul_f32_e32 v24, v63, v63
	v_fma_f32 v24, v62, v62, v24
	v_add_f32_e32 v25, v23, v24
	v_add_f32_e32 v22, v22, v25
	v_add_f32_e32 v16, v16, v22
	v_mul_f32_e32 v20, v65, v65
	v_fma_f32 v20, v64, v64, v20
	v_mul_f32_e32 v21, v67, v67
	v_fma_f32 v21, v66, v66, v21
	v_add_f32_e32 v22, v20, v21
	v_mul_f32_e32 v23, v69, v69
	v_fma_f32 v23, v68, v68, v23
	v_mul_f32_e32 v24, v71, v71
	v_fma_f32 v24, v70, v70, v24
	v_add_f32_e32 v25, v23, v24
	v_add_f32_e32 v22, v22, v25
	v_add_f32_e32 v16, v16, v22
	v_cvt_pk_bf16_f32 v40, v40, v41
	v_cvt_pk_bf16_f32 v41, v42, v43
	v_cvt_pk_bf16_f32 v42, v44, v45
	v_cvt_pk_bf16_f32 v43, v46, v47
	v_cvt_pk_bf16_f32 v48, v48, v49
	v_cvt_pk_bf16_f32 v49, v50, v51
	v_cvt_pk_bf16_f32 v50, v52, v53
	v_cvt_pk_bf16_f32 v51, v54, v55
	v_cvt_pk_bf16_f32 v56, v56, v57
	v_cvt_pk_bf16_f32 v57, v58, v59
	v_cvt_pk_bf16_f32 v58, v60, v61
	v_cvt_pk_bf16_f32 v59, v62, v63
	v_cvt_pk_bf16_f32 v64, v64, v65
	v_cvt_pk_bf16_f32 v65, v66, v67
	v_cvt_pk_bf16_f32 v66, v68, v69
	v_cvt_pk_bf16_f32 v67, v70, v71
	s_nop 1
	v_mfma_f32_16x16x32_bf16 v[0:3], v[40:43], v[72:75], 0
	v_mfma_f32_16x16x32_bf16 v[0:3], v[48:51], v[76:79], v[0:3]
	v_mfma_f32_16x16x32_bf16 v[0:3], v[56:59], v[80:83], v[0:3]
	v_mfma_f32_16x16x32_bf16 v[0:3], v[64:67], v[84:87], v[0:3]
	s_and_saveexec_b64 s[8:9], vcc
	global_load_dwordx4 v[40:43], v[10:11], off offset:112
	global_load_dwordx4 v[44:47], v[10:11], off offset:128
	global_load_dwordx4 v[48:51], v[10:11], off offset:240
	global_load_dwordx4 v[52:55], v[10:11], off offset:256
	global_load_dwordx4 v[56:59], v[10:11], off offset:368
	global_load_dwordx4 v[60:63], v[10:11], off offset:384
	global_load_dwordx4 v[64:67], v[10:11], off offset:496
	global_load_dwordx4 v[68:71], v[10:11], off offset:512
	s_or_b64 exec, exec, s[8:9]
	global_load_dwordx4 v[72:75], v[12:13], off offset:128
	global_load_dwordx4 v[76:79], v[12:13], off offset:192
	global_load_dwordx4 v[80:83], v[12:13], off offset:256
	global_load_dwordx4 v[84:87], v[12:13], off offset:320
	s_waitcnt vmcnt(0)
	v_mul_f32_e32 v20, v41, v41
	v_fma_f32 v20, v40, v40, v20
	v_mul_f32_e32 v21, v43, v43
	v_fma_f32 v21, v42, v42, v21
	v_add_f32_e32 v22, v20, v21
	v_mul_f32_e32 v23, v45, v45
	v_fma_f32 v23, v44, v44, v23
	v_mul_f32_e32 v24, v47, v47
	v_fma_f32 v24, v46, v46, v24
	v_add_f32_e32 v25, v23, v24
	v_add_f32_e32 v22, v22, v25
	v_add_f32_e32 v16, v16, v22
	v_mul_f32_e32 v20, v49, v49
	v_fma_f32 v20, v48, v48, v20
	v_mul_f32_e32 v21, v51, v51
	v_fma_f32 v21, v50, v50, v21
	v_add_f32_e32 v22, v20, v21
	v_mul_f32_e32 v23, v53, v53
	v_fma_f32 v23, v52, v52, v23
	v_mul_f32_e32 v24, v55, v55
	v_fma_f32 v24, v54, v54, v24
	v_add_f32_e32 v25, v23, v24
	v_add_f32_e32 v22, v22, v25
	v_add_f32_e32 v16, v16, v22
	v_mul_f32_e32 v20, v57, v57
	v_fma_f32 v20, v56, v56, v20
	v_mul_f32_e32 v21, v59, v59
	v_fma_f32 v21, v58, v58, v21
	v_add_f32_e32 v22, v20, v21
	v_mul_f32_e32 v23, v61, v61
	v_fma_f32 v23, v60, v60, v23
	v_mul_f32_e32 v24, v63, v63
	v_fma_f32 v24, v62, v62, v24
	v_add_f32_e32 v25, v23, v24
	v_add_f32_e32 v22, v22, v25
	v_add_f32_e32 v16, v16, v22
	v_mul_f32_e32 v20, v65, v65
	v_fma_f32 v20, v64, v64, v20
	v_mul_f32_e32 v21, v67, v67
	v_fma_f32 v21, v66, v66, v21
	v_add_f32_e32 v22, v20, v21
	v_mul_f32_e32 v23, v69, v69
	v_fma_f32 v23, v68, v68, v23
	v_mul_f32_e32 v24, v71, v71
	v_fma_f32 v24, v70, v70, v24
	v_add_f32_e32 v25, v23, v24
	v_add_f32_e32 v22, v22, v25
	v_add_f32_e32 v16, v16, v22
	v_cvt_pk_bf16_f32 v40, v40, v41
	v_cvt_pk_bf16_f32 v41, v42, v43
	v_cvt_pk_bf16_f32 v42, v44, v45
	v_cvt_pk_bf16_f32 v43, v46, v47
	v_cvt_pk_bf16_f32 v48, v48, v49
	v_cvt_pk_bf16_f32 v49, v50, v51
	v_cvt_pk_bf16_f32 v50, v52, v53
	v_cvt_pk_bf16_f32 v51, v54, v55
	v_cvt_pk_bf16_f32 v56, v56, v57
	v_cvt_pk_bf16_f32 v57, v58, v59
	v_cvt_pk_bf16_f32 v58, v60, v61
	v_cvt_pk_bf16_f32 v59, v62, v63
	v_cvt_pk_bf16_f32 v64, v64, v65
	v_cvt_pk_bf16_f32 v65, v66, v67
	v_cvt_pk_bf16_f32 v66, v68, v69
	v_cvt_pk_bf16_f32 v67, v70, v71
	s_nop 1
	v_mfma_f32_16x16x32_bf16 v[0:3], v[40:43], v[72:75], v[0:3]
	v_mfma_f32_16x16x32_bf16 v[0:3], v[48:51], v[76:79], v[0:3]
	v_mfma_f32_16x16x32_bf16 v[0:3], v[56:59], v[80:83], v[0:3]
	v_mfma_f32_16x16x32_bf16 v[0:3], v[64:67], v[84:87], v[0:3]
	s_nop 1

.LBB0_809:
	v_mov_b32_e32 v14, v190
	s_ashr_i32 s39, s38, 31
	s_lshl_b64 s[8:9], s[38:39], 12
	v_and_b32_e32 v15, 15, v14
	v_lshrrev_b32_e32 v0, 1, v14
	v_and_b32_e32 v2, 24, v0
	v_lshlrev_b32_e32 v0, 12, v15
	v_mov_b32_e32 v1, v129
	v_lshl_add_u64 v[0:1], s[8:9], 0, v[0:1]
	v_add_u32_e32 v2, s21, v2
	v_mov_b32_e32 v3, v129
	v_readlane_b32 s8, v237, 41
	v_lshl_add_u64 v[0:1], v[2:3], 1, v[0:1]
	v_readlane_b32 s9, v237, 42
	v_lshlrev_b32_e32 v128, 13, v15
	v_mov_b32_e32 v16, 0
	v_lshl_add_u64 v[10:11], s[8:9], 0, v[0:1]
	v_readlane_b32 s8, v237, 43
	v_lshl_add_u64 v[0:1], v[2:3], 2, v[128:129]
	v_readlane_b32 s9, v237, 44
	v_cmp_gt_u32_e32 vcc, 8, v15
	s_movk_i32 s1, 0xffe0
	v_lshl_add_u64 v[12:13], s[8:9], 0, v[0:1]
	v_mov_b32_e32 v40, 0
	v_mov_b32_e32 v41, 0
	v_mov_b32_e32 v42, 0
	v_mov_b32_e32 v43, 0
	v_mov_b32_e32 v44, 0
	v_mov_b32_e32 v45, 0
	v_mov_b32_e32 v46, 0
	v_mov_b32_e32 v47, 0
	v_mov_b32_e32 v48, 0
	v_mov_b32_e32 v49, 0
	v_mov_b32_e32 v50, 0
	v_mov_b32_e32 v51, 0
	v_mov_b32_e32 v52, 0
	v_mov_b32_e32 v53, 0
	v_mov_b32_e32 v54, 0
	v_mov_b32_e32 v55, 0
	v_mov_b32_e32 v56, 0
	v_mov_b32_e32 v57, 0
	v_mov_b32_e32 v58, 0
	v_mov_b32_e32 v59, 0
	v_mov_b32_e32 v60, 0
	v_mov_b32_e32 v61, 0
	v_mov_b32_e32 v62, 0
	v_mov_b32_e32 v63, 0
	v_mov_b32_e32 v64, 0
	v_mov_b32_e32 v65, 0
	v_mov_b32_e32 v66, 0
	v_mov_b32_e32 v67, 0
	v_mov_b32_e32 v68, 0
	v_mov_b32_e32 v69, 0
	v_mov_b32_e32 v70, 0
	v_mov_b32_e32 v71, 0
	s_and_saveexec_b64 s[8:9], vcc
	global_load_dwordx4 v[40:43], v[12:13], off offset:-128
	global_load_dwordx4 v[44:47], v[12:13], off offset:-112
	global_load_dwordx4 v[48:51], v[12:13], off
	global_load_dwordx4 v[52:55], v[12:13], off offset:16
	global_load_dwordx4 v[56:59], v[12:13], off offset:128
	global_load_dwordx4 v[60:63], v[12:13], off offset:144
	global_load_dwordx4 v[64:67], v[12:13], off offset:256
	global_load_dwordx4 v[68:71], v[12:13], off offset:272
	s_or_b64 exec, exec, s[8:9]
	global_load_dwordx4 v[72:75], v[10:11], off offset:-192
	global_load_dwordx4 v[76:79], v[10:11], off offset:-128
	global_load_dwordx4 v[80:83], v[10:11], off offset:-64
	global_load_dwordx4 v[84:87], v[10:11], off
	s_waitcnt vmcnt(0)
	v_mul_f32_e32 v20, v41, v41
	v_fma_f32 v20, v40, v40, v20
	v_mul_f32_e32 v21, v43, v43
	v_fma_f32 v21, v42, v42, v21
	v_add_f32_e32 v22, v20, v21
	v_mul_f32_e32 v23, v45, v45
	v_fma_f32 v23, v44, v44, v23
	v_mul_f32_e32 v24, v47, v47
	v_fma_f32 v24, v46, v46, v24
	v_add_f32_e32 v25, v23, v24
	v_add_f32_e32 v22, v22, v25
	v_add_f32_e32 v16, v16, v22
	v_mul_f32_e32 v20, v49, v49
	v_fma_f32 v20, v48, v48, v20
	v_mul_f32_e32 v21, v51, v51
	v_fma_f32 v21, v50, v50, v21
	v_add_f32_e32 v22, v20, v21
	v_mul_f32_e32 v23, v53, v53
	v_fma_f32 v23, v52, v52, v23
	v_mul_f32_e32 v24, v55, v55
	v_fma_f32 v24, v54, v54, v24
	v_add_f32_e32 v25, v23, v24
	v_add_f32_e32 v22, v22, v25
	v_add_f32_e32 v16, v16, v22
	v_mul_f32_e32 v20, v57, v57
	v_fma_f32 v20, v56, v56, v20
	v_mul_f32_e32 v21, v59, v59
	v_fma_f32 v21, v58, v58, v21
	v_add_f32_e32 v22, v20, v21
	v_mul_f32_e32 v23, v61, v61
	v_fma_f32 v23, v60, v60, v23
	v_mul_f32_e32 v24, v63, v63
	v_fma_f32 v24, v62, v62, v24
	v_add_f32_e32 v25, v23, v24
	v_add_f32_e32 v22, v22, v25
	v_add_f32_e32 v16, v16, v22
	v_mul_f32_e32 v20, v65, v65
	v_fma_f32 v20, v64, v64, v20
	v_mul_f32_e32 v21, v67, v67
	v_fma_f32 v21, v66, v66, v21
	v_add_f32_e32 v22, v20, v21
	v_mul_f32_e32 v23, v69, v69
	v_fma_f32 v23, v68, v68, v23
	v_mul_f32_e32 v24, v71, v71
	v_fma_f32 v24, v70, v70, v24
	v_add_f32_e32 v25, v23, v24
	v_add_f32_e32 v22, v22, v25
	v_add_f32_e32 v16, v16, v22
	v_cvt_pk_bf16_f32 v40, v40, v41
	v_cvt_pk_bf16_f32 v41, v42, v43
	v_cvt_pk_bf16_f32 v42, v44, v45
	v_cvt_pk_bf16_f32 v43, v46, v47
	v_cvt_pk_bf16_f32 v48, v48, v49
	v_cvt_pk_bf16_f32 v49, v50, v51
	v_cvt_pk_bf16_f32 v50, v52, v53
	v_cvt_pk_bf16_f32 v51, v54, v55
	v_cvt_pk_bf16_f32 v56, v56, v57
	v_cvt_pk_bf16_f32 v57, v58, v59
	v_cvt_pk_bf16_f32 v58, v60, v61
	v_cvt_pk_bf16_f32 v59, v62, v63
	v_cvt_pk_bf16_f32 v64, v64, v65
	v_cvt_pk_bf16_f32 v65, v66, v67
	v_cvt_pk_bf16_f32 v66, v68, v69
	v_cvt_pk_bf16_f32 v67, v70, v71
	s_nop 1
	v_mfma_f32_16x16x32_bf16 v[0:3], v[40:43], v[72:75], 0
	v_mfma_f32_16x16x32_bf16 v[0:3], v[48:51], v[76:79], v[0:3]
	v_mfma_f32_16x16x32_bf16 v[0:3], v[56:59], v[80:83], v[0:3]
	v_mfma_f32_16x16x32_bf16 v[0:3], v[64:67], v[84:87], v[0:3]
	s_and_saveexec_b64 s[8:9], vcc
	global_load_dwordx4 v[40:43], v[12:13], off offset:384
	global_load_dwordx4 v[44:47], v[12:13], off offset:400
	global_load_dwordx4 v[48:51], v[12:13], off offset:512
	global_load_dwordx4 v[52:55], v[12:13], off offset:528
	global_load_dwordx4 v[56:59], v[12:13], off offset:640
	global_load_dwordx4 v[60:63], v[12:13], off offset:656
	global_load_dwordx4 v[64:67], v[12:13], off offset:768
	global_load_dwordx4 v[68:71], v[12:13], off offset:784
	s_or_b64 exec, exec, s[8:9]
	global_load_dwordx4 v[72:75], v[10:11], off offset:64
	global_load_dwordx4 v[76:79], v[10:11], off offset:128
	global_load_dwordx4 v[80:83], v[10:11], off offset:192
	global_load_dwordx4 v[84:87], v[10:11], off offset:256
	s_waitcnt vmcnt(0)
	v_mul_f32_e32 v20, v41, v41
	v_fma_f32 v20, v40, v40, v20
	v_mul_f32_e32 v21, v43, v43
	v_fma_f32 v21, v42, v42, v21
	v_add_f32_e32 v22, v20, v21
	v_mul_f32_e32 v23, v45, v45
	v_fma_f32 v23, v44, v44, v23
	v_mul_f32_e32 v24, v47, v47
	v_fma_f32 v24, v46, v46, v24
	v_add_f32_e32 v25, v23, v24
	v_add_f32_e32 v22, v22, v25
	v_add_f32_e32 v16, v16, v22
	v_mul_f32_e32 v20, v49, v49
	v_fma_f32 v20, v48, v48, v20
	v_mul_f32_e32 v21, v51, v51
	v_fma_f32 v21, v50, v50, v21
	v_add_f32_e32 v22, v20, v21
	v_mul_f32_e32 v23, v53, v53
	v_fma_f32 v23, v52, v52, v23
	v_mul_f32_e32 v24, v55, v55
	v_fma_f32 v24, v54, v54, v24
	v_add_f32_e32 v25, v23, v24
	v_add_f32_e32 v22, v22, v25
	v_add_f32_e32 v16, v16, v22
	v_mul_f32_e32 v20, v57, v57
	v_fma_f32 v20, v56, v56, v20
	v_mul_f32_e32 v21, v59, v59
	v_fma_f32 v21, v58, v58, v21
	v_add_f32_e32 v22, v20, v21
	v_mul_f32_e32 v23, v61, v61
	v_fma_f32 v23, v60, v60, v23
	v_mul_f32_e32 v24, v63, v63
	v_fma_f32 v24, v62, v62, v24
	v_add_f32_e32 v25, v23, v24
	v_add_f32_e32 v22, v22, v25
	v_add_f32_e32 v16, v16, v22
	v_mul_f32_e32 v20, v65, v65
	v_fma_f32 v20, v64, v64, v20
	v_mul_f32_e32 v21, v67, v67
	v_fma_f32 v21, v66, v66, v21
	v_add_f32_e32 v22, v20, v21
	v_mul_f32_e32 v23, v69, v69
	v_fma_f32 v23, v68, v68, v23
	v_mul_f32_e32 v24, v71, v71
	v_fma_f32 v24, v70, v70, v24
	v_add_f32_e32 v25, v23, v24
	v_add_f32_e32 v22, v22, v25
	v_add_f32_e32 v16, v16, v22
	v_cvt_pk_bf16_f32 v40, v40, v41
	v_cvt_pk_bf16_f32 v41, v42, v43
	v_cvt_pk_bf16_f32 v42, v44, v45
	v_cvt_pk_bf16_f32 v43, v46, v47
	v_cvt_pk_bf16_f32 v48, v48, v49
	v_cvt_pk_bf16_f32 v49, v50, v51
	v_cvt_pk_bf16_f32 v50, v52, v53
	v_cvt_pk_bf16_f32 v51, v54, v55
	v_cvt_pk_bf16_f32 v56, v56, v57
	v_cvt_pk_bf16_f32 v57, v58, v59
	v_cvt_pk_bf16_f32 v58, v60, v61
	v_cvt_pk_bf16_f32 v59, v62, v63
	v_cvt_pk_bf16_f32 v64, v64, v65
	v_cvt_pk_bf16_f32 v65, v66, v67
	v_cvt_pk_bf16_f32 v66, v68, v69
	v_cvt_pk_bf16_f32 v67, v70, v71
	s_nop 1
	v_mfma_f32_16x16x32_bf16 v[0:3], v[40:43], v[72:75], v[0:3]
	v_mfma_f32_16x16x32_bf16 v[0:3], v[48:51], v[76:79], v[0:3]
	v_mfma_f32_16x16x32_bf16 v[0:3], v[56:59], v[80:83], v[0:3]
	v_mfma_f32_16x16x32_bf16 v[0:3], v[64:67], v[84:87], v[0:3]
	s_nop 1

.LBB0_1363:
	v_mov_b32_e32 v12, v190
	v_readlane_b32 s6, v238, 4
	v_and_b32_e32 v13, 15, v12
	v_lshrrev_b32_e32 v0, 1, v12
	v_and_or_b32 v6, v0, 24, s59
	v_lshlrev_b32_e32 v128, 11, v13
	v_readlane_b32 s7, v238, 5
	v_ashrrev_i32_e32 v7, 31, v6
	v_cmp_gt_u32_e32 vcc, 8, v13
	v_lshl_add_u64 v[0:1], s[6:7], 0, v[128:129]
	v_lshl_add_u64 v[8:9], v[6:7], 2, v[0:1]
	s_ashr_i32 s5, s4, 31
	s_lshl_b64 s[6:7], s[4:5], 10
	v_lshlrev_b32_e32 v1, 9, v13
	s_add_u32 s6, s0, s6
	s_addc_u32 s7, s1, s7
	v_lshlrev_b32_e32 v128, 1, v1
	v_lshl_add_u64 v[10:11], s[6:7], 0, v[128:129]
	v_lshl_add_u64 v[10:11], v[6:7], 1, v[10:11]
	v_mov_b32_e32 v22, 0
	v_mov_b32_e32 v23, 0
	v_mov_b32_e32 v24, 0
	v_mov_b32_e32 v25, 0
	v_mov_b32_e32 v26, 0
	v_mov_b32_e32 v27, 0
	v_mov_b32_e32 v28, 0
	v_mov_b32_e32 v29, 0
	v_mov_b32_e32 v30, 0
	v_mov_b32_e32 v31, 0
	v_mov_b32_e32 v32, 0
	v_mov_b32_e32 v33, 0
	v_mov_b32_e32 v34, 0
	v_mov_b32_e32 v35, 0
	v_mov_b32_e32 v36, 0
	v_mov_b32_e32 v37, 0
	s_and_saveexec_b64 s[6:7], vcc
	global_load_dwordx4 v[22:25], v[8:9], off
	global_load_dwordx4 v[26:29], v[8:9], off offset:16
	global_load_dwordx4 v[30:33], v[8:9], off offset:128
	global_load_dwordx4 v[34:37], v[8:9], off offset:144
	s_or_b64 exec, exec, s[6:7]
	global_load_dwordx4 v[38:41], v[10:11], off
	global_load_dwordx4 v[42:45], v[10:11], off offset:64
	s_waitcnt vmcnt(0)
	v_cvt_pk_bf16_f32 v22, v22, v23
	v_cvt_pk_bf16_f32 v23, v24, v25
	v_cvt_pk_bf16_f32 v24, v26, v27
	v_cvt_pk_bf16_f32 v25, v28, v29
	v_cvt_pk_bf16_f32 v30, v30, v31
	v_cvt_pk_bf16_f32 v31, v32, v33
	v_cvt_pk_bf16_f32 v32, v34, v35
	v_cvt_pk_bf16_f32 v33, v36, v37
	s_nop 1
	v_mfma_f32_16x16x32_bf16 v[0:3], v[22:25], v[38:41], 0
	v_mfma_f32_16x16x32_bf16 v[0:3], v[30:33], v[42:45], v[0:3]
	v_readlane_b32 s6, v240, 20
	v_readlane_b32 s7, v240, 21
	s_nop 2
	v_and_b32_e32 v4, 63, v12
	v_lshl_add_u32 v5, v4, 4, s33
	v_cmp_gt_u32_e32 vcc, 32, v4
	s_nop 1
	ds_write_b128 v5, v[0:3]
	s_and_b64 s[6:7], s[6:7], vcc
	v_mov_b32_e32 v2, 0
	v_mov_b32_e32 v3, 0
	v_mov_b32_e32 v0, 0
	v_mov_b32_e32 v1, 0
	s_waitcnt lgkmcnt(0)
	s_barrier
	s_and_saveexec_b64 s[8:9], s[6:7]
	s_cbranch_execz .LBB0_1369
	v_lshl_add_u32 v10, v4, 4, 0
	ds_read_b128 v[0:3], v10
	s_waitcnt lgkmcnt(0)
	v_pk_add_f32 v[4:5], v[2:3], 0 op_sel_hi:[1,0]
	v_pk_add_f32 v[6:7], v[0:1], 0 op_sel_hi:[1,0]
	ds_read_b128 v[0:3], v10 offset:1024
	s_waitcnt lgkmcnt(0)
	v_pk_add_f32 v[4:5], v[2:3], v[4:5]
	v_pk_add_f32 v[6:7], v[0:1], v[6:7]
	ds_read_b128 v[0:3], v10 offset:2048
	s_waitcnt lgkmcnt(0)
	v_pk_add_f32 v[4:5], v[2:3], v[4:5]
	v_pk_add_f32 v[6:7], v[0:1], v[6:7]
	ds_read_b128 v[0:3], v10 offset:3072
	s_waitcnt lgkmcnt(0)
	v_pk_add_f32 v[4:5], v[2:3], v[4:5]
	v_pk_add_f32 v[6:7], v[0:1], v[6:7]
	ds_read_b128 v[0:3], v10 offset:4096
	s_waitcnt lgkmcnt(0)
	v_pk_add_f32 v[4:5], v[2:3], v[4:5]
	v_pk_add_f32 v[6:7], v[0:1], v[6:7]
	ds_read_b128 v[0:3], v10 offset:5120
	s_waitcnt lgkmcnt(0)
	v_pk_add_f32 v[4:5], v[2:3], v[4:5]
	v_pk_add_f32 v[6:7], v[0:1], v[6:7]
	ds_read_b128 v[0:3], v10 offset:6144
	s_waitcnt lgkmcnt(0)
	v_pk_add_f32 v[8:9], v[2:3], v[4:5]
	ds_read_b128 v[2:5], v10 offset:7168
	v_pk_add_f32 v[6:7], v[0:1], v[6:7]
	s_waitcnt lgkmcnt(0)
	v_pk_add_f32 v[0:1], v[4:5], v[8:9]
	v_pk_add_f32 v[2:3], v[2:3], v[6:7]
